# two-level release: only XCC leaders poll the top word, each leader then bumps a per-XCC generation word polled by its 31 locals
# baseline (speedup 1.0000x reference)
_Z14fwd_megakernel6Params:
	s_load_dwordx4 s[68:71], s[0:1], 0x80
	s_load_dwordx16 s[36:51], s[0:1], 0x0
	s_load_dwordx2 s[34:35], s[0:1], 0x90
	s_load_dwordx16 s[16:31], s[0:1], 0x40
	s_mov_b32 s12, s2
	s_waitcnt lgkmcnt(0)
	s_add_u32 s14, s70, 0x1f7a0000
	v_and_b32_e32 v1, 0x3ff, v0
	s_addc_u32 s15, s71, 0
	v_writelane_b32 v244, s16, 0
	s_sub_i32 s2, s35, s34
	s_cmp_lt_i32 s2, 2
	v_writelane_b32 v244, s17, 1
	v_writelane_b32 v244, s18, 2
	v_writelane_b32 v244, s19, 3
	v_writelane_b32 v244, s20, 4
	v_writelane_b32 v244, s21, 5
	v_writelane_b32 v244, s22, 6
	v_writelane_b32 v244, s23, 7
	v_writelane_b32 v244, s24, 8
	v_writelane_b32 v244, s25, 9
	v_writelane_b32 v244, s26, 10
	v_writelane_b32 v244, s27, 11
	v_writelane_b32 v244, s28, 12
	v_writelane_b32 v244, s29, 13
	v_writelane_b32 v244, s30, 14
	v_readfirstlane_b32 s10, v1
	v_writelane_b32 v244, s31, 15
	s_cbranch_scc1 .LBB0_14
	v_or_b32_e32 v2, s12, v1
	v_cmp_eq_u32_e32 vcc, 0, v2
	s_and_saveexec_b64 s[2:3], vcc
	s_cbranch_execz .LBB0_3
	v_mov_b32_e32 v2, 0
	global_store_dword v2, v2, s[14:15] sc1
	global_store_dword v2, v2, s[68:69] sc1
	global_store_dword v2, v2, s[68:69] offset:256 sc1
	global_store_dword v2, v2, s[68:69] offset:512 sc1
	global_store_dword v2, v2, s[68:69] offset:768 sc1
	global_store_dword v2, v2, s[68:69] offset:1024 sc1
	global_store_dword v2, v2, s[68:69] offset:1280 sc1
	global_store_dword v2, v2, s[68:69] offset:1536 sc1
	global_store_dword v2, v2, s[68:69] offset:1792 sc1
	v_mov_b32_e32 v3, 0x1000
	global_store_dword v3, v2, s[68:69] sc1
	global_store_dword v3, v2, s[68:69] offset:256 sc1
	global_store_dword v3, v2, s[68:69] offset:512 sc1
	global_store_dword v3, v2, s[68:69] offset:768 sc1
	global_store_dword v3, v2, s[68:69] offset:1024 sc1
	global_store_dword v3, v2, s[68:69] offset:1280 sc1
	global_store_dword v3, v2, s[68:69] offset:1536 sc1
	global_store_dword v3, v2, s[68:69] offset:1792 sc1
	global_store_dword v3, v2, s[68:69] offset:128 sc1
	global_store_dword v3, v2, s[68:69] offset:384 sc1
	global_store_dword v3, v2, s[68:69] offset:640 sc1
	global_store_dword v3, v2, s[68:69] offset:896 sc1
	global_store_dword v3, v2, s[68:69] offset:1152 sc1
	global_store_dword v3, v2, s[68:69] offset:1408 sc1
	global_store_dword v3, v2, s[68:69] offset:1664 sc1
	global_store_dword v3, v2, s[68:69] offset:1920 sc1
	s_waitcnt vmcnt(0)
	v_mov_b32_e32 v3, 0x13579bdf
	global_store_dword v2, v3, s[14:15] offset:64 sc1

.Lcen_done:
	v_min_u32_e32 v2, 1, v2
	v_min_u32_e32 v3, 1, v3
	v_min_u32_e32 v4, 1, v4
	v_min_u32_e32 v5, 1, v5
	v_min_u32_e32 v6, 1, v6
	v_min_u32_e32 v7, 1, v7
	v_min_u32_e32 v8, 1, v8
	v_min_u32_e32 v9, 1, v9
	v_add_u32_e32 v1, v2, v3
	v_add_u32_e32 v1, v1, v4
	v_add_u32_e32 v1, v1, v5
	v_add_u32_e32 v1, v1, v6
	v_add_u32_e32 v1, v1, v7
	v_add_u32_e32 v1, v1, v8
	v_add_u32_e32 v1, v1, v9
	s_nop 0
	v_readfirstlane_b32 s101, v1
	s_getreg_b32 s5, hwreg(HW_REG_XCC_ID, 0, 4)
	s_lshl_b32 s5, s5, 8
	s_add_u32 s5, s5, 0x1000
	v_mov_b32_e32 v0, s5
	global_load_dword v1, v0, s[68:69] sc1
	s_waitcnt vmcnt(0)
	v_readfirstlane_b32 s98, v1
	s_nop 3
	s_sub_i32 s4, 1, s34
	s_getreg_b32 s5, hwreg(HW_REG_XCC_ID, 0, 4)
	s_mul_i32 s6, s98, s4
	s_lshl_b32 s5, s5, 8
	v_mov_b32_e32 v0, s5
	v_mov_b32_e32 v1, 1
	global_atomic_add v1, v0, v1, s[68:69] sc0
	s_mul_i32 s7, s101, s4
	s_add_u32 s5, s5, 0x1080
	s_waitcnt vmcnt(0)
	v_add_u32_e32 v1, 1, v1
	v_cmp_eq_u32_e32 vcc, s6, v1
	s_cbranch_vccz .Lgb_half_s0
	buffer_wbl2 sc1
	s_waitcnt vmcnt(0)
	v_mov_b32_e32 v0, 0
	v_mov_b32_e32 v1, 1
	global_atomic_add v1, v0, v1, s[14:15] sc0
	buffer_inv sc1
	s_waitcnt vmcnt(0)
	v_add_u32_e32 v1, 1, v1
	v_cmp_eq_u32_e32 vcc, s7, v1
	s_cbranch_vccnz .Lgb_rel_s0
.Lgb_tspin_s0:
	global_load_dword v1, v0, s[14:15] sc1
	s_waitcnt vmcnt(0)
	v_cmp_gt_u32_e32 vcc, s7, v1
	s_cbranch_vccz .Lgb_rel_s0
	s_sleep 1
	s_branch .Lgb_tspin_s0
.Lgb_rel_s0:
	v_mov_b32_e32 v0, s5
	v_mov_b32_e32 v1, 1
	global_atomic_add v0, v1, s[68:69]
	s_branch .Lgb_done_s0

.Lgb_inv_s0:
	buffer_inv sc1
	v_mov_b32_e32 v0, s5
.Lgb_spin_s0:
	global_load_dword v1, v0, s[68:69] sc1
	s_waitcnt vmcnt(0)
	v_cmp_gt_u32_e32 vcc, s4, v1
	s_cbranch_vccz .Lgb_done_s0
	s_sleep 1
	s_branch .Lgb_spin_s0

.LBB0_151:
	s_cmp_lt_i32 s35, 3
	s_cbranch_scc1 .LBB0_160
	v_mbcnt_lo_u32_b32 v0, -1, 0
	v_mbcnt_hi_u32_b32 v0, -1, v0
	s_waitcnt vmcnt(0) lgkmcnt(0)
	s_waitcnt vmcnt(0) lgkmcnt(0)
	v_add_u32_e32 v0, s84, v0
	v_cmp_gt_u32_e32 vcc, 64, v0
	s_barrier
	s_and_saveexec_b64 s[0:1], vcc
	s_cbranch_execz .LBB0_159
	s_waitcnt vmcnt(0)
	v_cmp_eq_u32_e32 vcc, 0, v0
	s_and_saveexec_b64 s[2:3], vcc
	s_cbranch_execz .LBB0_158
	s_sub_i32 s4, 2, s34
	s_getreg_b32 s5, hwreg(HW_REG_XCC_ID, 0, 4)
	s_mul_i32 s6, s98, s4
	s_lshl_b32 s5, s5, 8
	v_mov_b32_e32 v0, s5
	v_mov_b32_e32 v1, 1
	global_atomic_add v1, v0, v1, s[68:69] sc0
	s_mul_i32 s7, s101, s4
	s_add_u32 s5, s5, 0x1080
	s_waitcnt vmcnt(0)
	v_add_u32_e32 v1, 1, v1
	v_cmp_eq_u32_e32 vcc, s6, v1
	s_cbranch_vccz .Lgb_half_s1
	buffer_wbl2 sc1
	s_waitcnt vmcnt(0)
	v_mov_b32_e32 v0, 0
	v_mov_b32_e32 v1, 1
	global_atomic_add v1, v0, v1, s[14:15] sc0
	buffer_inv sc1
	s_waitcnt vmcnt(0)
	v_add_u32_e32 v1, 1, v1
	v_cmp_eq_u32_e32 vcc, s7, v1
	s_cbranch_vccnz .Lgb_rel_s1

.LBB0_211:
	s_cmp_eq_u32 s100, 1
	s_cbranch_scc1 .Ldil_ret12
	s_cmp_lt_i32 s35, 4
	s_cbranch_scc1 .LBB0_220
	v_mbcnt_lo_u32_b32 v0, -1, 0
	v_mbcnt_hi_u32_b32 v0, -1, v0
	s_waitcnt vmcnt(0) lgkmcnt(0)
	s_waitcnt lgkmcnt(0)
	v_add_u32_e32 v0, s84, v0
	v_cmp_gt_u32_e32 vcc, 64, v0
	s_barrier
	s_and_saveexec_b64 s[0:1], vcc
	s_cbranch_execz .LBB0_219
	s_waitcnt vmcnt(0)
	s_waitcnt vmcnt(0)
	v_cmp_eq_u32_e32 vcc, 0, v0
	s_and_saveexec_b64 s[2:3], vcc
	s_cbranch_execz .LBB0_218
	s_sub_i32 s4, 3, s34
	s_getreg_b32 s5, hwreg(HW_REG_XCC_ID, 0, 4)
	s_mul_i32 s6, s98, s4
	s_lshl_b32 s5, s5, 8
	v_mov_b32_e32 v0, s5
	v_mov_b32_e32 v1, 1
	global_atomic_add v1, v0, v1, s[68:69] sc0
	s_mul_i32 s7, s101, s4
	s_add_u32 s5, s5, 0x1080
	s_waitcnt vmcnt(0)
	v_add_u32_e32 v1, 1, v1
	v_cmp_eq_u32_e32 vcc, s6, v1
	s_cbranch_vccz .Lgb_half_s2
	buffer_wbl2 sc1
	s_waitcnt vmcnt(0)
	v_mov_b32_e32 v0, 0
	v_mov_b32_e32 v1, 1
	global_atomic_add v1, v0, v1, s[14:15] sc0
	buffer_inv sc1
	s_waitcnt vmcnt(0)
	v_add_u32_e32 v1, 1, v1
	v_cmp_eq_u32_e32 vcc, s7, v1
	s_cbranch_vccnz .Lgb_rel_s2

.LBB0_245:
	s_cmp_lt_i32 s35, 5
	s_cbranch_scc1 .LBB0_254
	v_mbcnt_lo_u32_b32 v0, -1, 0
	v_mbcnt_hi_u32_b32 v0, -1, v0
	s_waitcnt vmcnt(0) lgkmcnt(0)
	s_waitcnt vmcnt(0) lgkmcnt(0)
	v_add_u32_e32 v0, s84, v0
	v_cmp_gt_u32_e32 vcc, 64, v0
	s_barrier
	s_and_saveexec_b64 s[0:1], vcc
	s_cbranch_execz .LBB0_253
	s_waitcnt vmcnt(0)
	v_cmp_eq_u32_e32 vcc, 0, v0
	s_and_saveexec_b64 s[2:3], vcc
	s_cbranch_execz .LBB0_252
	s_sub_i32 s4, 4, s34
	s_getreg_b32 s5, hwreg(HW_REG_XCC_ID, 0, 4)
	s_mul_i32 s6, s98, s4
	s_lshl_b32 s5, s5, 8
	v_mov_b32_e32 v0, s5
	v_mov_b32_e32 v1, 1
	global_atomic_add v1, v0, v1, s[68:69] sc0
	s_mul_i32 s7, s101, s4
	s_add_u32 s5, s5, 0x1080
	s_waitcnt vmcnt(0)
	v_add_u32_e32 v1, 1, v1
	v_cmp_eq_u32_e32 vcc, s6, v1
	s_cbranch_vccz .Lgb_half_s3
	buffer_wbl2 sc1
	s_waitcnt vmcnt(0)
	v_mov_b32_e32 v0, 0
	v_mov_b32_e32 v1, 1
	global_atomic_add v1, v0, v1, s[14:15] sc0
	buffer_inv sc1
	s_waitcnt vmcnt(0)
	v_add_u32_e32 v1, 1, v1
	v_cmp_eq_u32_e32 vcc, s7, v1
	s_cbranch_vccnz .Lgb_rel_s3

.LBB0_289:
	s_cmp_eq_u32 s99, 1
	s_cbranch_scc1 .Lmla_ret14
	s_cmp_lt_i32 s35, 6
	s_cbranch_scc1 .LBB0_298
	v_mbcnt_lo_u32_b32 v0, -1, 0
	v_mbcnt_hi_u32_b32 v0, -1, v0
	s_waitcnt vmcnt(0) lgkmcnt(0)
	s_waitcnt lgkmcnt(0)
	v_add_u32_e32 v0, s84, v0
	v_cmp_gt_u32_e32 vcc, 64, v0
	s_barrier
	s_and_saveexec_b64 s[0:1], vcc
	s_cbranch_execz .LBB0_297
	s_waitcnt vmcnt(0)
	s_waitcnt vmcnt(0)
	v_cmp_eq_u32_e32 vcc, 0, v0
	s_and_saveexec_b64 s[2:3], vcc
	s_cbranch_execz .LBB0_296
	s_sub_i32 s4, 5, s34
	s_getreg_b32 s5, hwreg(HW_REG_XCC_ID, 0, 4)
	s_mul_i32 s6, s98, s4
	s_lshl_b32 s5, s5, 8
	v_mov_b32_e32 v0, s5
	v_mov_b32_e32 v1, 1
	global_atomic_add v1, v0, v1, s[68:69] sc0
	s_mul_i32 s7, s101, s4
	s_add_u32 s5, s5, 0x1080
	s_waitcnt vmcnt(0)
	v_add_u32_e32 v1, 1, v1
	v_cmp_eq_u32_e32 vcc, s6, v1
	s_cbranch_vccz .Lgb_half_s4
	buffer_wbl2 sc1
	s_waitcnt vmcnt(0)
	v_mov_b32_e32 v0, 0
	v_mov_b32_e32 v1, 1
	global_atomic_add v1, v0, v1, s[14:15] sc0
	buffer_inv sc1
	s_waitcnt vmcnt(0)
	v_add_u32_e32 v1, 1, v1
	v_cmp_eq_u32_e32 vcc, s7, v1
	s_cbranch_vccnz .Lgb_rel_s4

.LBB0_302:
	s_or_b64 exec, exec, s[2:3]
	s_cmp_lt_u32 s35, 7
	s_cbranch_scc1 .LBB0_311
	v_mbcnt_lo_u32_b32 v0, -1, 0
	v_mbcnt_hi_u32_b32 v0, -1, v0
	s_waitcnt vmcnt(0) lgkmcnt(0)
	s_waitcnt lgkmcnt(0)
	v_add_u32_e32 v0, s84, v0
	v_cmp_gt_u32_e32 vcc, 64, v0
	s_barrier
	s_and_saveexec_b64 s[0:1], vcc
	s_cbranch_execz .LBB0_310
	s_waitcnt vmcnt(0)
	s_waitcnt vmcnt(0)
	v_cmp_eq_u32_e32 vcc, 0, v0
	s_and_saveexec_b64 s[2:3], vcc
	s_cbranch_execz .LBB0_309
	s_sub_i32 s4, 6, s34
	s_getreg_b32 s5, hwreg(HW_REG_XCC_ID, 0, 4)
	s_mul_i32 s6, s98, s4
	s_lshl_b32 s5, s5, 8
	v_mov_b32_e32 v0, s5
	v_mov_b32_e32 v1, 1
	global_atomic_add v1, v0, v1, s[68:69] sc0
	s_mul_i32 s7, s101, s4
	s_add_u32 s5, s5, 0x1080
	s_waitcnt vmcnt(0)
	v_add_u32_e32 v1, 1, v1
	v_cmp_eq_u32_e32 vcc, s6, v1
	s_cbranch_vccz .Lgb_half_s5
	buffer_wbl2 sc1
	s_waitcnt vmcnt(0)
	v_mov_b32_e32 v0, 0
	v_mov_b32_e32 v1, 1
	global_atomic_add v1, v0, v1, s[14:15] sc0
	buffer_inv sc1
	s_waitcnt vmcnt(0)
	v_add_u32_e32 v1, 1, v1
	v_cmp_eq_u32_e32 vcc, s7, v1
	s_cbranch_vccnz .Lgb_rel_s5

.LBB0_327:
	s_cmp_lt_i32 s35, 8
	s_cbranch_scc1 .LBB0_336
	v_mbcnt_lo_u32_b32 v0, -1, 0
	v_mbcnt_hi_u32_b32 v0, -1, v0
	s_waitcnt vmcnt(0) lgkmcnt(0)
	s_waitcnt vmcnt(0) lgkmcnt(0)
	v_add_u32_e32 v0, s84, v0
	v_cmp_gt_u32_e32 vcc, 64, v0
	s_barrier
	s_and_saveexec_b64 s[0:1], vcc
	s_cbranch_execz .LBB0_335
	s_waitcnt vmcnt(0)
	v_cmp_eq_u32_e32 vcc, 0, v0
	s_and_saveexec_b64 s[2:3], vcc
	s_cbranch_execz .LBB0_334
	s_sub_i32 s4, 7, s34
	s_getreg_b32 s5, hwreg(HW_REG_XCC_ID, 0, 4)
	s_mul_i32 s6, s98, s4
	s_lshl_b32 s5, s5, 8
	v_mov_b32_e32 v0, s5
	v_mov_b32_e32 v1, 1
	global_atomic_add v1, v0, v1, s[68:69] sc0
	s_mul_i32 s7, s101, s4
	s_add_u32 s5, s5, 0x1080
	s_waitcnt vmcnt(0)
	v_add_u32_e32 v1, 1, v1
	v_cmp_eq_u32_e32 vcc, s6, v1
	s_cbranch_vccz .Lgb_half_s6
	buffer_wbl2 sc1
	s_waitcnt vmcnt(0)
	v_mov_b32_e32 v0, 0
	v_mov_b32_e32 v1, 1
	global_atomic_add v1, v0, v1, s[14:15] sc0
	buffer_inv sc1
	s_waitcnt vmcnt(0)
	v_add_u32_e32 v1, 1, v1
	v_cmp_eq_u32_e32 vcc, s7, v1
	s_cbranch_vccnz .Lgb_rel_s6

.LBB0_348:
	s_or_b64 exec, exec, s[2:3]
	s_cmp_lt_i32 s35, 9
	s_cbranch_scc1 .LBB0_357
	v_mbcnt_lo_u32_b32 v0, -1, 0
	v_mbcnt_hi_u32_b32 v0, -1, v0
	s_waitcnt vmcnt(0) lgkmcnt(0)
	s_waitcnt lgkmcnt(0)
	v_add_u32_e32 v0, s84, v0
	v_cmp_gt_u32_e32 vcc, 64, v0
	s_barrier
	s_and_saveexec_b64 s[0:1], vcc
	s_cbranch_execz .LBB0_356
	s_waitcnt vmcnt(0)
	s_waitcnt vmcnt(0)
	v_cmp_eq_u32_e32 vcc, 0, v0
	s_and_saveexec_b64 s[2:3], vcc
	s_cbranch_execz .LBB0_355
	s_sub_i32 s4, 8, s34
	s_getreg_b32 s5, hwreg(HW_REG_XCC_ID, 0, 4)
	s_mul_i32 s6, s98, s4
	s_lshl_b32 s5, s5, 8
	v_mov_b32_e32 v0, s5
	v_mov_b32_e32 v1, 1
	global_atomic_add v1, v0, v1, s[68:69] sc0
	s_mul_i32 s7, s101, s4
	s_add_u32 s5, s5, 0x1080
	s_waitcnt vmcnt(0)
	v_add_u32_e32 v1, 1, v1
	v_cmp_eq_u32_e32 vcc, s6, v1
	s_cbranch_vccz .Lgb_half_s7
	buffer_wbl2 sc1
	s_waitcnt vmcnt(0)
	v_mov_b32_e32 v0, 0
	v_mov_b32_e32 v1, 1
	global_atomic_add v1, v0, v1, s[14:15] sc0
	buffer_inv sc1
	s_waitcnt vmcnt(0)
	v_add_u32_e32 v1, 1, v1
	v_cmp_eq_u32_e32 vcc, s7, v1
	s_cbranch_vccnz .Lgb_rel_s7

.LBB0_373:
	s_cmp_lt_i32 s35, 10
	s_cbranch_scc1 .LBB0_382
	v_mbcnt_lo_u32_b32 v0, -1, 0
	v_mbcnt_hi_u32_b32 v0, -1, v0
	s_waitcnt vmcnt(0) lgkmcnt(0)
	s_waitcnt vmcnt(0) lgkmcnt(0)
	v_add_u32_e32 v0, s84, v0
	v_cmp_gt_u32_e32 vcc, 64, v0
	s_barrier
	s_and_saveexec_b64 s[0:1], vcc
	s_cbranch_execz .LBB0_381
	s_waitcnt vmcnt(0)
	v_cmp_eq_u32_e32 vcc, 0, v0
	s_and_saveexec_b64 s[2:3], vcc
	s_cbranch_execz .LBB0_380
	s_sub_i32 s4, 9, s34
	s_getreg_b32 s5, hwreg(HW_REG_XCC_ID, 0, 4)
	s_mul_i32 s6, s98, s4
	s_lshl_b32 s5, s5, 8
	v_mov_b32_e32 v0, s5
	v_mov_b32_e32 v1, 1
	global_atomic_add v1, v0, v1, s[68:69] sc0
	s_mul_i32 s7, s101, s4
	s_add_u32 s5, s5, 0x1080
	s_waitcnt vmcnt(0)
	v_add_u32_e32 v1, 1, v1
	v_cmp_eq_u32_e32 vcc, s6, v1
	s_cbranch_vccz .Lgb_half_s8
	buffer_wbl2 sc1
	s_waitcnt vmcnt(0)
	v_mov_b32_e32 v0, 0
	v_mov_b32_e32 v1, 1
	global_atomic_add v1, v0, v1, s[14:15] sc0
	buffer_inv sc1
	s_waitcnt vmcnt(0)
	v_add_u32_e32 v1, 1, v1
	v_cmp_eq_u32_e32 vcc, s7, v1
	s_cbranch_vccnz .Lgb_rel_s8

.LBB0_398:
	s_cmp_lt_i32 s35, 11
	s_cbranch_scc1 .LBB0_407
	v_mbcnt_lo_u32_b32 v0, -1, 0
	v_mbcnt_hi_u32_b32 v0, -1, v0
	s_waitcnt vmcnt(0) lgkmcnt(0)
	s_waitcnt vmcnt(0) lgkmcnt(0)
	v_add_u32_e32 v0, s84, v0
	v_cmp_gt_u32_e32 vcc, 64, v0
	s_barrier
	s_and_saveexec_b64 s[0:1], vcc
	s_cbranch_execz .LBB0_406
	s_waitcnt vmcnt(0)
	v_cmp_eq_u32_e32 vcc, 0, v0
	s_and_saveexec_b64 s[2:3], vcc
	s_cbranch_execz .LBB0_405
	s_sub_i32 s4, 10, s34
	s_getreg_b32 s5, hwreg(HW_REG_XCC_ID, 0, 4)
	s_mul_i32 s6, s98, s4
	s_lshl_b32 s5, s5, 8
	v_mov_b32_e32 v0, s5
	v_mov_b32_e32 v1, 1
	global_atomic_add v1, v0, v1, s[68:69] sc0
	s_mul_i32 s7, s101, s4
	s_add_u32 s5, s5, 0x1080
	s_waitcnt vmcnt(0)
	v_add_u32_e32 v1, 1, v1
	v_cmp_eq_u32_e32 vcc, s6, v1
	s_cbranch_vccz .Lgb_half_s9
	buffer_wbl2 sc1
	s_waitcnt vmcnt(0)
	v_mov_b32_e32 v0, 0
	v_mov_b32_e32 v1, 1
	global_atomic_add v1, v0, v1, s[14:15] sc0
	buffer_inv sc1
	s_waitcnt vmcnt(0)
	v_add_u32_e32 v1, 1, v1
	v_cmp_eq_u32_e32 vcc, s7, v1
	s_cbranch_vccnz .Lgb_rel_s9

.LBB0_442:
	s_or_b64 exec, exec, s[0:1]
	s_cmp_lt_i32 s35, 12
	s_cbranch_scc1 .LBB0_451
	v_mbcnt_lo_u32_b32 v0, -1, 0
	v_mbcnt_hi_u32_b32 v0, -1, v0
	s_waitcnt vmcnt(0) lgkmcnt(0)
	s_waitcnt lgkmcnt(0)
	v_add_u32_e32 v0, s84, v0
	v_cmp_gt_u32_e32 vcc, 64, v0
	s_barrier
	s_and_saveexec_b64 s[0:1], vcc
	s_cbranch_execz .LBB0_450
	s_waitcnt vmcnt(0)
	s_waitcnt vmcnt(0)
	v_cmp_eq_u32_e32 vcc, 0, v0
	s_and_saveexec_b64 s[2:3], vcc
	s_cbranch_execz .LBB0_449
	s_sub_i32 s4, 11, s34
	s_getreg_b32 s5, hwreg(HW_REG_XCC_ID, 0, 4)
	s_mul_i32 s6, s98, s4
	s_lshl_b32 s5, s5, 8
	v_mov_b32_e32 v0, s5
	v_mov_b32_e32 v1, 1
	global_atomic_add v1, v0, v1, s[68:69] sc0
	s_mul_i32 s7, s101, s4
	s_add_u32 s5, s5, 0x1080
	s_waitcnt vmcnt(0)
	v_add_u32_e32 v1, 1, v1
	v_cmp_eq_u32_e32 vcc, s6, v1
	s_cbranch_vccz .Lgb_half_s10
	buffer_wbl2 sc1
	s_waitcnt vmcnt(0)
	v_mov_b32_e32 v0, 0
	v_mov_b32_e32 v1, 1
	global_atomic_add v1, v0, v1, s[14:15] sc0
	buffer_inv sc1
	s_waitcnt vmcnt(0)
	v_add_u32_e32 v1, 1, v1
	v_cmp_eq_u32_e32 vcc, s7, v1
	s_cbranch_vccnz .Lgb_rel_s10

.LBB0_531:
	s_cmp_lt_i32 s35, 13
	s_cbranch_scc1 .LBB0_540
	v_mbcnt_lo_u32_b32 v0, -1, 0
	v_mbcnt_hi_u32_b32 v0, -1, v0
	s_waitcnt vmcnt(0) lgkmcnt(0)
	s_waitcnt vmcnt(0) lgkmcnt(0)
	v_add_u32_e32 v0, s84, v0
	v_cmp_gt_u32_e32 vcc, 64, v0
	s_barrier
	s_and_saveexec_b64 s[0:1], vcc
	s_cbranch_execz .LBB0_539
	s_waitcnt vmcnt(0)
	v_cmp_eq_u32_e32 vcc, 0, v0
	s_and_saveexec_b64 s[2:3], vcc
	s_cbranch_execz .LBB0_538
	s_sub_i32 s4, 12, s34
	s_getreg_b32 s5, hwreg(HW_REG_XCC_ID, 0, 4)
	s_mul_i32 s6, s98, s4
	s_lshl_b32 s5, s5, 8
	v_mov_b32_e32 v0, s5
	v_mov_b32_e32 v1, 1
	global_atomic_add v1, v0, v1, s[68:69] sc0
	s_mul_i32 s7, s101, s4
	s_add_u32 s5, s5, 0x1080
	s_waitcnt vmcnt(0)
	v_add_u32_e32 v1, 1, v1
	v_cmp_eq_u32_e32 vcc, s6, v1
	s_cbranch_vccz .Lgb_half_s11
	buffer_wbl2 sc1
	s_waitcnt vmcnt(0)
	v_mov_b32_e32 v0, 0
	v_mov_b32_e32 v1, 1
	global_atomic_add v1, v0, v1, s[14:15] sc0
	buffer_inv sc1
	s_waitcnt vmcnt(0)
	v_add_u32_e32 v1, 1, v1
	v_cmp_eq_u32_e32 vcc, s7, v1
	s_cbranch_vccnz .Lgb_rel_s11

.Ldil_ret12:
.LBB0_590:
	s_cmp_lt_i32 s35, 14
	s_cbranch_scc1 .LBB0_599
	v_mbcnt_lo_u32_b32 v0, -1, 0
	v_mbcnt_hi_u32_b32 v0, -1, v0
	s_waitcnt vmcnt(0) lgkmcnt(0)
	s_waitcnt lgkmcnt(0)
	v_add_u32_e32 v0, s84, v0
	v_cmp_gt_u32_e32 vcc, 64, v0
	s_barrier
	s_and_saveexec_b64 s[0:1], vcc
	s_cbranch_execz .LBB0_598
	s_waitcnt vmcnt(0)
	s_waitcnt vmcnt(0)
	v_cmp_eq_u32_e32 vcc, 0, v0
	s_and_saveexec_b64 s[2:3], vcc
	s_cbranch_execz .LBB0_597
	s_sub_i32 s4, 13, s34
	s_getreg_b32 s5, hwreg(HW_REG_XCC_ID, 0, 4)
	s_mul_i32 s6, s98, s4
	s_lshl_b32 s5, s5, 8
	v_mov_b32_e32 v0, s5
	v_mov_b32_e32 v1, 1
	global_atomic_add v1, v0, v1, s[68:69] sc0
	s_mul_i32 s7, s101, s4
	s_add_u32 s5, s5, 0x1080
	s_waitcnt vmcnt(0)
	v_add_u32_e32 v1, 1, v1
	v_cmp_eq_u32_e32 vcc, s6, v1
	s_cbranch_vccz .Lgb_half_s12
	buffer_wbl2 sc1
	s_waitcnt vmcnt(0)
	v_mov_b32_e32 v0, 0
	v_mov_b32_e32 v1, 1
	global_atomic_add v1, v0, v1, s[14:15] sc0
	buffer_inv sc1
	s_waitcnt vmcnt(0)
	v_add_u32_e32 v1, 1, v1
	v_cmp_eq_u32_e32 vcc, s7, v1
	s_cbranch_vccnz .Lgb_rel_s12

.LBB0_624:
	s_cmp_lt_i32 s35, 15
	s_cbranch_scc1 .LBB0_633
	v_mbcnt_lo_u32_b32 v0, -1, 0
	v_mbcnt_hi_u32_b32 v0, -1, v0
	s_waitcnt vmcnt(0) lgkmcnt(0)
	s_waitcnt vmcnt(0) lgkmcnt(0)
	v_add_u32_e32 v0, s84, v0
	v_cmp_gt_u32_e32 vcc, 64, v0
	s_barrier
	s_and_saveexec_b64 s[0:1], vcc
	s_cbranch_execz .LBB0_632
	s_waitcnt vmcnt(0)
	v_cmp_eq_u32_e32 vcc, 0, v0
	s_and_saveexec_b64 s[2:3], vcc
	s_cbranch_execz .LBB0_631
	s_sub_i32 s4, 14, s34
	s_getreg_b32 s5, hwreg(HW_REG_XCC_ID, 0, 4)
	s_mul_i32 s6, s98, s4
	s_lshl_b32 s5, s5, 8
	v_mov_b32_e32 v0, s5
	v_mov_b32_e32 v1, 1
	global_atomic_add v1, v0, v1, s[68:69] sc0
	s_mul_i32 s7, s101, s4
	s_add_u32 s5, s5, 0x1080
	s_waitcnt vmcnt(0)
	v_add_u32_e32 v1, 1, v1
	v_cmp_eq_u32_e32 vcc, s6, v1
	s_cbranch_vccz .Lgb_half_s13
	buffer_wbl2 sc1
	s_waitcnt vmcnt(0)
	v_mov_b32_e32 v0, 0
	v_mov_b32_e32 v1, 1
	global_atomic_add v1, v0, v1, s[14:15] sc0
	buffer_inv sc1
	s_waitcnt vmcnt(0)
	v_add_u32_e32 v1, 1, v1
	v_cmp_eq_u32_e32 vcc, s7, v1
	s_cbranch_vccnz .Lgb_rel_s13

.Lmla_ret14:
.LBB0_668:
	s_cmp_lt_i32 s35, 16
	s_cbranch_scc1 .LBB0_677
	v_mbcnt_lo_u32_b32 v0, -1, 0
	v_mbcnt_hi_u32_b32 v0, -1, v0
	s_waitcnt vmcnt(0) lgkmcnt(0)
	s_waitcnt lgkmcnt(0)
	v_add_u32_e32 v0, s84, v0
	v_cmp_gt_u32_e32 vcc, 64, v0
	s_barrier
	s_and_saveexec_b64 s[0:1], vcc
	s_cbranch_execz .LBB0_676
	s_waitcnt vmcnt(0)
	s_waitcnt vmcnt(0)
	v_cmp_eq_u32_e32 vcc, 0, v0
	s_and_saveexec_b64 s[2:3], vcc
	s_cbranch_execz .LBB0_675
	s_sub_i32 s4, 15, s34
	s_getreg_b32 s5, hwreg(HW_REG_XCC_ID, 0, 4)
	s_mul_i32 s6, s98, s4
	s_lshl_b32 s5, s5, 8
	v_mov_b32_e32 v0, s5
	v_mov_b32_e32 v1, 1
	global_atomic_add v1, v0, v1, s[68:69] sc0
	s_mul_i32 s7, s101, s4
	s_add_u32 s5, s5, 0x1080
	s_waitcnt vmcnt(0)
	v_add_u32_e32 v1, 1, v1
	v_cmp_eq_u32_e32 vcc, s6, v1
	s_cbranch_vccz .Lgb_half_s14
	buffer_wbl2 sc1
	s_waitcnt vmcnt(0)
	v_mov_b32_e32 v0, 0
	v_mov_b32_e32 v1, 1
	global_atomic_add v1, v0, v1, s[14:15] sc0
	buffer_inv sc1
	s_waitcnt vmcnt(0)
	v_add_u32_e32 v1, 1, v1
	v_cmp_eq_u32_e32 vcc, s7, v1
	s_cbranch_vccnz .Lgb_rel_s14

.LBB0_681:
	s_or_b64 exec, exec, s[2:3]
	s_cmp_lt_u32 s35, 17
	s_cbranch_scc1 .LBB0_690
	v_mbcnt_lo_u32_b32 v0, -1, 0
	v_mbcnt_hi_u32_b32 v0, -1, v0
	s_waitcnt vmcnt(0) lgkmcnt(0)
	s_waitcnt lgkmcnt(0)
	v_add_u32_e32 v0, s84, v0
	v_cmp_gt_u32_e32 vcc, 64, v0
	s_barrier
	s_and_saveexec_b64 s[0:1], vcc
	s_cbranch_execz .LBB0_689
	s_waitcnt vmcnt(0)
	s_waitcnt vmcnt(0)
	v_cmp_eq_u32_e32 vcc, 0, v0
	s_and_saveexec_b64 s[2:3], vcc
	s_cbranch_execz .LBB0_688
	s_sub_i32 s4, 16, s34
	s_getreg_b32 s5, hwreg(HW_REG_XCC_ID, 0, 4)
	s_mul_i32 s6, s98, s4
	s_lshl_b32 s5, s5, 8
	v_mov_b32_e32 v0, s5
	v_mov_b32_e32 v1, 1
	global_atomic_add v1, v0, v1, s[68:69] sc0
	s_mul_i32 s7, s101, s4
	s_add_u32 s5, s5, 0x1080
	s_waitcnt vmcnt(0)
	v_add_u32_e32 v1, 1, v1
	v_cmp_eq_u32_e32 vcc, s6, v1
	s_cbranch_vccz .Lgb_half_s15
	buffer_wbl2 sc1
	s_waitcnt vmcnt(0)
	v_mov_b32_e32 v0, 0
	v_mov_b32_e32 v1, 1
	global_atomic_add v1, v0, v1, s[14:15] sc0
	buffer_inv sc1
	s_waitcnt vmcnt(0)
	v_add_u32_e32 v1, 1, v1
	v_cmp_eq_u32_e32 vcc, s7, v1
	s_cbranch_vccnz .Lgb_rel_s15

.LBB0_706:
	s_cmp_lt_i32 s35, 18
	s_cbranch_scc1 .LBB0_715
	v_mbcnt_lo_u32_b32 v0, -1, 0
	v_mbcnt_hi_u32_b32 v0, -1, v0
	s_waitcnt vmcnt(0) lgkmcnt(0)
	s_waitcnt vmcnt(0) lgkmcnt(0)
	v_add_u32_e32 v0, s84, v0
	v_cmp_gt_u32_e32 vcc, 64, v0
	s_barrier
	s_and_saveexec_b64 s[0:1], vcc
	s_cbranch_execz .LBB0_714
	s_waitcnt vmcnt(0)
	v_cmp_eq_u32_e32 vcc, 0, v0
	s_and_saveexec_b64 s[2:3], vcc
	s_cbranch_execz .LBB0_713
	s_sub_i32 s4, 17, s34
	s_getreg_b32 s5, hwreg(HW_REG_XCC_ID, 0, 4)
	s_mul_i32 s6, s98, s4
	s_lshl_b32 s5, s5, 8
	v_mov_b32_e32 v0, s5
	v_mov_b32_e32 v1, 1
	global_atomic_add v1, v0, v1, s[68:69] sc0
	s_mul_i32 s7, s101, s4
	s_add_u32 s5, s5, 0x1080
	s_waitcnt vmcnt(0)
	v_add_u32_e32 v1, 1, v1
	v_cmp_eq_u32_e32 vcc, s6, v1
	s_cbranch_vccz .Lgb_half_s16
	buffer_wbl2 sc1
	s_waitcnt vmcnt(0)
	v_mov_b32_e32 v0, 0
	v_mov_b32_e32 v1, 1
	global_atomic_add v1, v0, v1, s[14:15] sc0
	buffer_inv sc1
	s_waitcnt vmcnt(0)
	v_add_u32_e32 v1, 1, v1
	v_cmp_eq_u32_e32 vcc, s7, v1
	s_cbranch_vccnz .Lgb_rel_s16

.LBB0_719:
	s_or_b64 exec, exec, s[0:1]
	s_cmp_lt_u32 s35, 19
	s_cbranch_scc1 .LBB0_728
	v_mbcnt_lo_u32_b32 v0, -1, 0
	v_mbcnt_hi_u32_b32 v0, -1, v0
	s_waitcnt vmcnt(0) lgkmcnt(0)
	s_nop 0
	v_add_u32_e32 v0, s84, v0
	v_cmp_gt_u32_e32 vcc, 64, v0
	s_barrier
	s_and_saveexec_b64 s[0:1], vcc
	s_cbranch_execz .LBB0_727
	s_waitcnt vmcnt(0)
	s_waitcnt vmcnt(0)
	v_cmp_eq_u32_e32 vcc, 0, v0
	s_and_saveexec_b64 s[2:3], vcc
	s_cbranch_execz .LBB0_726
	s_sub_i32 s4, 18, s34
	s_getreg_b32 s5, hwreg(HW_REG_XCC_ID, 0, 4)
	s_mul_i32 s6, s98, s4
	s_lshl_b32 s5, s5, 8
	v_mov_b32_e32 v0, s5
	v_mov_b32_e32 v1, 1
	global_atomic_add v1, v0, v1, s[68:69] sc0
	s_mul_i32 s7, s101, s4
	s_add_u32 s5, s5, 0x1080
	s_waitcnt vmcnt(0)
	v_add_u32_e32 v1, 1, v1
	v_cmp_eq_u32_e32 vcc, s6, v1
	s_cbranch_vccz .Lgb_half_s17
	buffer_wbl2 sc1
	s_waitcnt vmcnt(0)
	v_mov_b32_e32 v0, 0
	v_mov_b32_e32 v1, 1
	global_atomic_add v1, v0, v1, s[14:15] sc0
	buffer_inv sc1
	s_waitcnt vmcnt(0)
	v_add_u32_e32 v1, 1, v1
	v_cmp_eq_u32_e32 vcc, s7, v1
	s_cbranch_vccnz .Lgb_rel_s17

.LBB0_744:
	s_cmp_lt_i32 s35, 20
	s_cbranch_scc1 .LBB0_753
	v_mbcnt_lo_u32_b32 v0, -1, 0
	v_mbcnt_hi_u32_b32 v0, -1, v0
	s_waitcnt vmcnt(0) lgkmcnt(0)
	s_waitcnt vmcnt(0) lgkmcnt(0)
	v_add_u32_e32 v0, s84, v0
	v_cmp_gt_u32_e32 vcc, 64, v0
	s_barrier
	s_and_saveexec_b64 s[0:1], vcc
	s_cbranch_execz .LBB0_752
	s_waitcnt vmcnt(0)
	v_cmp_eq_u32_e32 vcc, 0, v0
	s_and_saveexec_b64 s[2:3], vcc
	s_cbranch_execz .LBB0_751
	s_sub_i32 s4, 19, s34
	s_getreg_b32 s5, hwreg(HW_REG_XCC_ID, 0, 4)
	s_mul_i32 s6, s98, s4
	s_lshl_b32 s5, s5, 8
	v_mov_b32_e32 v0, s5
	v_mov_b32_e32 v1, 1
	global_atomic_add v1, v0, v1, s[68:69] sc0
	s_mul_i32 s7, s101, s4
	s_add_u32 s5, s5, 0x1080
	s_waitcnt vmcnt(0)
	v_add_u32_e32 v1, 1, v1
	v_cmp_eq_u32_e32 vcc, s6, v1
	s_cbranch_vccz .Lgb_half_s18
	buffer_wbl2 sc1
	s_waitcnt vmcnt(0)
	v_mov_b32_e32 v0, 0
	v_mov_b32_e32 v1, 1
	global_atomic_add v1, v0, v1, s[14:15] sc0
	buffer_inv sc1
	s_waitcnt vmcnt(0)
	v_add_u32_e32 v1, 1, v1
	v_cmp_eq_u32_e32 vcc, s7, v1
	s_cbranch_vccnz .Lgb_rel_s18

.LBB0_769:
	s_cmp_lt_i32 s35, 21
	s_cbranch_scc1 .LBB0_778
	v_mbcnt_lo_u32_b32 v0, -1, 0
	v_mbcnt_hi_u32_b32 v0, -1, v0
	s_waitcnt vmcnt(0) lgkmcnt(0)
	s_waitcnt vmcnt(0) lgkmcnt(0)
	v_add_u32_e32 v0, s84, v0
	v_cmp_gt_u32_e32 vcc, 64, v0
	s_barrier
	s_and_saveexec_b64 s[0:1], vcc
	s_cbranch_execz .LBB0_777
	s_waitcnt vmcnt(0)
	v_cmp_eq_u32_e32 vcc, 0, v0
	s_and_saveexec_b64 s[2:3], vcc
	s_cbranch_execz .LBB0_776
	s_sub_i32 s4, 20, s34
	s_getreg_b32 s5, hwreg(HW_REG_XCC_ID, 0, 4)
	s_mul_i32 s6, s98, s4
	s_lshl_b32 s5, s5, 8
	v_mov_b32_e32 v0, s5
	v_mov_b32_e32 v1, 1
	global_atomic_add v1, v0, v1, s[68:69] sc0
	s_mul_i32 s7, s101, s4
	s_add_u32 s5, s5, 0x1080
	s_waitcnt vmcnt(0)
	v_add_u32_e32 v1, 1, v1
	v_cmp_eq_u32_e32 vcc, s6, v1
	s_cbranch_vccz .Lgb_half_s19
	buffer_wbl2 sc1
	s_waitcnt vmcnt(0)
	v_mov_b32_e32 v0, 0
	v_mov_b32_e32 v1, 1
	global_atomic_add v1, v0, v1, s[14:15] sc0
	buffer_inv sc1
	s_waitcnt vmcnt(0)
	v_add_u32_e32 v1, 1, v1
	v_cmp_eq_u32_e32 vcc, s7, v1
	s_cbranch_vccnz .Lgb_rel_s19

.LBB0_782:
	s_or_b64 exec, exec, s[0:1]
	s_cmp_lt_u32 s35, 22
	s_cbranch_scc1 .LBB0_791
	v_mbcnt_lo_u32_b32 v0, -1, 0
	v_mbcnt_hi_u32_b32 v0, -1, v0
	s_waitcnt vmcnt(0) lgkmcnt(0)
	s_waitcnt lgkmcnt(0)
	v_add_u32_e32 v0, s84, v0
	v_cmp_gt_u32_e32 vcc, 64, v0
	s_barrier
	s_and_saveexec_b64 s[0:1], vcc
	s_cbranch_execz .LBB0_790
	s_waitcnt vmcnt(0)
	s_waitcnt vmcnt(0)
	v_cmp_eq_u32_e32 vcc, 0, v0
	s_and_saveexec_b64 s[2:3], vcc
	s_cbranch_execz .LBB0_789
	s_sub_i32 s4, 21, s34
	s_getreg_b32 s5, hwreg(HW_REG_XCC_ID, 0, 4)
	s_mul_i32 s6, s98, s4
	s_lshl_b32 s5, s5, 8
	v_mov_b32_e32 v0, s5
	v_mov_b32_e32 v1, 1
	global_atomic_add v1, v0, v1, s[68:69] sc0
	s_mul_i32 s7, s101, s4
	s_add_u32 s5, s5, 0x1080
	s_waitcnt vmcnt(0)
	v_add_u32_e32 v1, 1, v1
	v_cmp_eq_u32_e32 vcc, s6, v1
	s_cbranch_vccz .Lgb_half_s20
	buffer_wbl2 sc1
	s_waitcnt vmcnt(0)
	v_mov_b32_e32 v0, 0
	v_mov_b32_e32 v1, 1
	global_atomic_add v1, v0, v1, s[14:15] sc0
	buffer_inv sc1
	s_waitcnt vmcnt(0)
	v_add_u32_e32 v1, 1, v1
	v_cmp_eq_u32_e32 vcc, s7, v1
	s_cbranch_vccnz .Lgb_rel_s20
